# NSA output section: four gate-tile loads issued together at the section top instead of four serial round trips
# speedup vs baseline: 1.0076x; 1.0076x over previous
; #define LAS __attribute__((address_space(3)))
; DI float bflo(unsigned w) { return __uint_as_float(w << 16); }
; DI float bfhi(unsigned w) { return __uint_as_float(w & 0xffff0000u); }
; DI void branch_fold(ASt& st, float gate, bool may_be_empty, LAS float* wsf, int lane) {
;     ...
;     for (int g4 = 0; g4 < 4; ++g4) { const f32x4 f = *(const LAS f32x4*)(wsf + 8 * g4 + 4 * hi);
; #pragma unroll
;         for (int k = 0; k < 4; ++k) { st.o0[4 * g4 + k] *= f[k]; st.o1[4 * g4 + k] *= f[k]; } }
; DI void nsa_unit(const Ctx& c0, int b, int g, int i, LAS unsigned char* lds) {
;     ...
;         for (int rg = 0; rg < 16; ++rg) { const unsigned w = OC[rg * 64]; ca0[rg] = (OACC[rg * 64] + st.o0[rg]) + bflo(w); ca1[rg] = (OACC[(16 + rg) * 64] + st.o1[rg]) + bfhi(w); }
;         __syncthreads();
;     }
;     ...
;     { const size_t g0 = ((size_t)b * SEQ + i * 64 + 32 * qh) * 512 + head * 64;
;       const bf16* nzg = (const bf16*)(c.ws + O_NZ) + g0; bf16* ong = (bf16*)(c.ws + O_ONSA) + g0;
;       LAS unsigned char* S = lds + A_OC + wid * 4096;
; #pragma unroll
;       for (int it = 0; it < 4; ++it) { const int rw = 8 * it + (lane >> 3), ch = lane & 7;
;           *(LAS u32x4*)(S + rw * 128 + ch * 16) = *(const u32x4*)(nzg + (size_t)rw * 512 + ch * 8); }
.LBB0_540:
	s_or_b64 exec, exec, s[12:13]
	s_or_b32 s3, s24, s33
	s_add_u32 s12, s8, s3
	s_addc_u32 s13, s9, 0
	s_lshl_b64 s[12:13], s[12:13], 9
	s_add_u32 s12, s12, s20
	s_addc_u32 s13, s13, 0
	s_lshl_b64 s[12:13], s[12:13], 1
	s_add_u32 s0, s0, s12
	s_addc_u32 s1, s1, s13
	v_mov_b32_e32 v135, v3
	v_lshl_add_u64 v[246:247], s[0:1], 0, v[134:135]
	s_mov_b64 s[98:99], 0xb500000
	v_lshl_add_u64 v[246:247], v[246:247], 0, s[98:99]
	v_lshl_add_u64 v[248:249], v[246:247], 0, v[126:127]
	global_load_dwordx4 v[230:233], v[248:249], off
	v_lshl_add_u64 v[248:249], v[246:247], 0, v[128:129]
	global_load_dwordx4 v[234:237], v[248:249], off
	v_lshl_add_u64 v[248:249], v[246:247], 0, v[130:131]
	global_load_dwordx4 v[238:241], v[248:249], off
	v_lshl_add_u64 v[248:249], v[246:247], 0, v[132:133]
	global_load_dwordx4 v[242:245], v[248:249], off
	s_waitcnt lgkmcnt(0)
	ds_read_b128 v[48:51], v205 offset:32768
	ds_read_b128 v[44:47], v205 offset:32800
	ds_read_b128 v[40:43], v205 offset:32832
	ds_read_b128 v[36:39], v205 offset:32864
	ds_read2st64_b32 v[52:53], v203 offset1:1
	ds_read2st64_b32 v[54:55], v214 offset0:144 offset1:145
	ds_read2st64_b32 v[56:57], v214 offset0:160 offset1:161
	s_waitcnt lgkmcnt(0)
	v_lshlrev_b32_e32 v2, 16, v52
	v_fma_f32 v1, v20, v48, v54
	v_add_f32_e32 v60, v1, v2
	v_fma_f32 v1, v4, v48, v56
	v_fmac_f32_e32 v55, v21, v49
	v_fmac_f32_e32 v57, v5, v49
	ds_read2st64_b32 v[4:5], v203 offset0:2 offset1:3
	ds_read2st64_b32 v[20:21], v214 offset0:146 offset1:147
	ds_read2st64_b32 v[48:49], v214 offset0:162 offset1:163
	v_and_b32_e32 v2, 0xffff0000, v52
	v_add_f32_e32 v59, v1, v2
	v_lshlrev_b32_e32 v1, 16, v53
	v_add_f32_e32 v58, v55, v1
	v_and_b32_e32 v1, 0xffff0000, v53
	v_add_f32_e32 v57, v57, v1
	s_waitcnt lgkmcnt(0)
	v_fma_f32 v1, v22, v50, v20
	v_lshlrev_b32_e32 v2, 16, v4
	v_add_f32_e32 v56, v1, v2
	v_fma_f32 v1, v6, v50, v48
	v_and_b32_e32 v2, 0xffff0000, v4
	v_add_f32_e32 v55, v1, v2
	v_fmac_f32_e32 v21, v23, v51
	v_lshlrev_b32_e32 v1, 16, v5
	v_add_f32_e32 v54, v21, v1
	v_fmac_f32_e32 v49, v7, v51
	v_and_b32_e32 v1, 0xffff0000, v5
	ds_read2st64_b32 v[4:5], v203 offset0:4 offset1:5
	ds_read2st64_b32 v[6:7], v214 offset0:148 offset1:149
	ds_read2st64_b32 v[20:21], v214 offset0:164 offset1:165
	v_add_f32_e32 v53, v49, v1
	s_waitcnt lgkmcnt(0)
	v_lshlrev_b32_e32 v2, 16, v4
	v_fma_f32 v1, v24, v44, v6
	v_add_f32_e32 v52, v1, v2
	v_fma_f32 v1, v8, v44, v20
	v_and_b32_e32 v2, 0xffff0000, v4
	v_add_f32_e32 v51, v1, v2
	v_fmac_f32_e32 v7, v25, v45
	v_lshlrev_b32_e32 v1, 16, v5
	v_add_f32_e32 v50, v7, v1
	v_and_b32_e32 v1, 0xffff0000, v5
	ds_read2st64_b32 v[4:5], v203 offset0:6 offset1:7
	ds_read2st64_b32 v[6:7], v214 offset0:150 offset1:151
	v_fmac_f32_e32 v21, v9, v45
	ds_read2st64_b32 v[8:9], v214 offset0:166 offset1:167
	v_add_f32_e32 v49, v21, v1
	s_waitcnt lgkmcnt(0)
	v_lshlrev_b32_e32 v2, 16, v4
	v_fma_f32 v1, v26, v46, v6
	v_add_f32_e32 v48, v1, v2
	v_fma_f32 v1, v10, v46, v8
	v_and_b32_e32 v2, 0xffff0000, v4
	v_add_f32_e32 v46, v1, v2
	v_fmac_f32_e32 v7, v27, v47
	v_lshlrev_b32_e32 v1, 16, v5
	v_add_f32_e32 v45, v7, v1
	v_fmac_f32_e32 v9, v11, v47
	v_and_b32_e32 v1, 0xffff0000, v5
	ds_read2st64_b32 v[4:5], v203 offset0:8 offset1:9
	ds_read2st64_b32 v[6:7], v214 offset0:152 offset1:153
	v_add_f32_e32 v44, v9, v1
	ds_read2st64_b32 v[8:9], v214 offset0:168 offset1:169
	s_waitcnt lgkmcnt(0)
	v_lshlrev_b32_e32 v2, 16, v4
	v_fma_f32 v1, v28, v40, v6
	v_add_f32_e32 v27, v1, v2
	v_fma_f32 v1, v12, v40, v8
	v_and_b32_e32 v2, 0xffff0000, v4
	v_add_f32_e32 v26, v1, v2
	v_fmac_f32_e32 v7, v29, v41
	v_lshlrev_b32_e32 v1, 16, v5
	v_add_f32_e32 v25, v7, v1
	v_fmac_f32_e32 v9, v13, v41
	v_and_b32_e32 v1, 0xffff0000, v5
	ds_read2st64_b32 v[4:5], v203 offset0:10 offset1:11
	ds_read2st64_b32 v[6:7], v214 offset0:154 offset1:155
	v_add_f32_e32 v24, v9, v1
	ds_read2st64_b32 v[8:9], v214 offset0:170 offset1:171
	s_waitcnt lgkmcnt(0)
	v_lshlrev_b32_e32 v2, 16, v4
	v_fma_f32 v1, v30, v42, v6
	v_add_f32_e32 v23, v1, v2
	v_fma_f32 v1, v14, v42, v8
	v_and_b32_e32 v2, 0xffff0000, v4
	v_add_f32_e32 v22, v1, v2
	v_fmac_f32_e32 v7, v31, v43
	v_lshlrev_b32_e32 v1, 16, v5
	v_add_f32_e32 v21, v7, v1
	v_fmac_f32_e32 v9, v15, v43
	v_and_b32_e32 v1, 0xffff0000, v5
	ds_read2st64_b32 v[4:5], v203 offset0:12 offset1:13
	ds_read2st64_b32 v[6:7], v214 offset0:156 offset1:157
	v_add_f32_e32 v15, v9, v1
	ds_read2st64_b32 v[8:9], v214 offset0:172 offset1:173
	s_waitcnt lgkmcnt(0)
	v_lshlrev_b32_e32 v2, 16, v4
	v_fma_f32 v1, v32, v36, v6
	v_add_f32_e32 v20, v1, v2
	v_fma_f32 v1, v16, v36, v8
	v_and_b32_e32 v2, 0xffff0000, v4
	v_add_f32_e32 v14, v1, v2
	v_fmac_f32_e32 v7, v33, v37
	v_lshlrev_b32_e32 v1, 16, v5
	v_add_f32_e32 v13, v7, v1
	v_fmac_f32_e32 v9, v17, v37
	v_and_b32_e32 v1, 0xffff0000, v5
	ds_read2st64_b32 v[4:5], v203 offset0:14 offset1:15
	ds_read2st64_b32 v[6:7], v214 offset0:158 offset1:159
	v_add_f32_e32 v12, v9, v1
	ds_read2st64_b32 v[8:9], v214 offset0:174 offset1:175
	s_waitcnt lgkmcnt(0)
	v_lshlrev_b32_e32 v2, 16, v4
	v_fma_f32 v1, v34, v38, v6
	v_add_f32_e32 v10, v1, v2
	v_fma_f32 v1, v18, v38, v8
	v_and_b32_e32 v2, 0xffff0000, v4
	v_add_f32_e32 v11, v1, v2
	v_fmac_f32_e32 v7, v35, v39
	v_lshlrev_b32_e32 v1, 16, v5
	v_add_f32_e32 v2, v7, v1
	v_fmac_f32_e32 v9, v19, v39
	v_and_b32_e32 v1, 0xffff0000, v5
	v_mov_b32_e32 v135, v3
	v_add_f32_e32 v1, v9, v1
	v_lshl_add_u64 v[8:9], s[0:1], 0, v[134:135]
	s_mov_b64 s[0:1], 0xb500000
	v_lshl_add_u64 v[16:17], v[8:9], 0, s[0:1]
	v_lshl_add_u64 v[4:5], v[16:17], 0, v[126:127]
	s_barrier
; #define LAS __attribute__((address_space(3)))
; #define LDS_WAIT() asm volatile("s_waitcnt lgkmcnt(0)" ::: "memory")
; DI unsigned cvtpk(float lo, float hi) { f32x2 v = {lo, hi}; bf16x2_t b = __builtin_convertvector(v, bf16x2_t); return __builtin_bit_cast(unsigned, b); }
; DI float bf2f(bf16 b) { return __uint_as_float(((unsigned)b) << 16); }
; DI float siluf_(float x) { return x / (1.f + __expf(-x)); }
; DI void nsa_unit(const Ctx& c0, int b, int g, int i, LAS unsigned char* lds) {
;     ...
;       for (int it = 0; it < 4; ++it) { const int rw = 8 * it + (lane >> 3), ch = lane & 7;
;           *(LAS u32x4*)(S + rw * 128 + ch * 16) = *(const u32x4*)(nzg + (size_t)rw * 512 + ch * 8); }
;       LDS_WAIT();
; #pragma unroll
;       for (int rg = 0; rg < 16; ++rg) { LAS bf16* e = (LAS bf16*)(S + ((rg & 3) + 8 * (rg >> 2) + 4 * hi) * 128 + r * 2);
;           const float z0 = bf2f(e[0]), z1 = bf2f(e[32]);
;           e[0] = (bf16)(cvtpk(ca0[rg] * siluf_(z0), 0.f) & 0xffffu);
;           e[32] = (bf16)(cvtpk(ca1[rg] * siluf_(z1), 0.f) & 0xffffu); }
	s_add_i32 s23, s23, 1
	s_cmp_eq_u32 s23, 4
	s_waitcnt vmcnt(0) lgkmcnt(0)
	ds_write_b128 v216, v[230:233]
	ds_write_b128 v217, v[234:237]
	ds_write_b128 v218, v[238:241]
	ds_write_b128 v219, v[242:245]
	s_waitcnt lgkmcnt(0)
	ds_read_u16 v4, v220
	ds_read_u16 v5, v220 offset:64
	s_waitcnt lgkmcnt(1)
	v_lshlrev_b32_e32 v4, 16, v4
	v_mul_f32_e32 v6, 0xbfb8aa3b, v4
	v_exp_f32_e32 v6, v6
	s_waitcnt lgkmcnt(0)
	v_lshlrev_b32_e32 v5, 16, v5
	v_add_f32_e32 v6, 1.0, v6
	v_div_scale_f32 v7, s[0:1], v6, v6, v4
	s_nop 0
	v_rcp_f32_e32 v7, v6
	s_nop 0
	v_mul_f32_e32 v4, v4, v7
	v_mul_f32_e32 v4, v60, v4
	v_cvt_pk_bf16_f32 v4, v4, s0
	ds_write_b16 v220, v4
	v_mul_f32_e32 v4, 0xbfb8aa3b, v5
	v_exp_f32_e32 v4, v4
	s_nop 0
	v_add_f32_e32 v4, 1.0, v4
	v_div_scale_f32 v6, s[0:1], v4, v4, v5
	s_nop 0
	v_rcp_f32_e32 v4, v4
	s_nop 0
	v_mul_f32_e32 v4, v5, v4
	v_mul_f32_e32 v4, v59, v4
	v_cvt_pk_bf16_f32 v4, v4, s0
	ds_write_b16 v220, v4 offset:64
	ds_read_u16 v4, v220 offset:128
	ds_read_u16 v5, v220 offset:192
	s_waitcnt lgkmcnt(1)
	v_lshlrev_b32_e32 v4, 16, v4
	v_mul_f32_e32 v6, 0xbfb8aa3b, v4
	v_exp_f32_e32 v6, v6
	s_waitcnt lgkmcnt(0)
	v_lshlrev_b32_e32 v5, 16, v5
	v_add_f32_e32 v6, 1.0, v6
	v_div_scale_f32 v7, s[0:1], v6, v6, v4
	s_nop 0
	v_rcp_f32_e32 v7, v6
	s_nop 0
	v_mul_f32_e32 v4, v4, v7
	v_mul_f32_e32 v4, v58, v4
	v_cvt_pk_bf16_f32 v4, v4, s0
	ds_write_b16 v220, v4 offset:128
	v_mul_f32_e32 v4, 0xbfb8aa3b, v5
	v_exp_f32_e32 v4, v4
	s_nop 0
	v_add_f32_e32 v4, 1.0, v4
	v_div_scale_f32 v6, s[0:1], v4, v4, v5
	s_nop 0
	v_rcp_f32_e32 v4, v4
	s_nop 0
	v_mul_f32_e32 v4, v5, v4
	v_mul_f32_e32 v4, v57, v4
	v_cvt_pk_bf16_f32 v4, v4, s0
	ds_write_b16 v220, v4 offset:192
	ds_read_u16 v4, v220 offset:256
	ds_read_u16 v5, v220 offset:320
	s_waitcnt lgkmcnt(1)
	v_lshlrev_b32_e32 v4, 16, v4
	v_mul_f32_e32 v6, 0xbfb8aa3b, v4
	v_exp_f32_e32 v6, v6
	s_waitcnt lgkmcnt(0)
	v_lshlrev_b32_e32 v5, 16, v5
	v_add_f32_e32 v6, 1.0, v6
	v_div_scale_f32 v7, s[0:1], v6, v6, v4
	s_nop 0
	v_rcp_f32_e32 v7, v6
	s_nop 0
	v_mul_f32_e32 v4, v4, v7
	v_mul_f32_e32 v4, v56, v4
	v_cvt_pk_bf16_f32 v4, v4, s0
	ds_write_b16 v220, v4 offset:256
	v_mul_f32_e32 v4, 0xbfb8aa3b, v5
	v_exp_f32_e32 v4, v4
	s_nop 0
	v_add_f32_e32 v4, 1.0, v4
	v_div_scale_f32 v6, s[0:1], v4, v4, v5
	s_nop 0
	v_rcp_f32_e32 v4, v4
	s_nop 0
	v_mul_f32_e32 v4, v5, v4
	v_mul_f32_e32 v4, v55, v4
	v_cvt_pk_bf16_f32 v4, v4, s0
	ds_write_b16 v220, v4 offset:320
	ds_read_u16 v4, v220 offset:384
	ds_read_u16 v5, v220 offset:448
	s_waitcnt lgkmcnt(1)
	v_lshlrev_b32_e32 v4, 16, v4
	v_mul_f32_e32 v6, 0xbfb8aa3b, v4
	v_exp_f32_e32 v6, v6
	s_waitcnt lgkmcnt(0)
	v_lshlrev_b32_e32 v5, 16, v5
	v_add_f32_e32 v6, 1.0, v6
	v_div_scale_f32 v7, s[0:1], v6, v6, v4
	s_nop 0
	v_rcp_f32_e32 v7, v6
	s_nop 0
	v_mul_f32_e32 v4, v4, v7
	v_mul_f32_e32 v4, v54, v4
	v_cvt_pk_bf16_f32 v4, v4, s0
	ds_write_b16 v220, v4 offset:384
	v_mul_f32_e32 v4, 0xbfb8aa3b, v5
	v_exp_f32_e32 v4, v4
	s_nop 0
	v_add_f32_e32 v4, 1.0, v4
	v_div_scale_f32 v6, s[0:1], v4, v4, v5
	s_nop 0
	v_rcp_f32_e32 v4, v4
	s_nop 0
	v_mul_f32_e32 v4, v5, v4
	v_mul_f32_e32 v4, v53, v4
	v_cvt_pk_bf16_f32 v4, v4, s0
	ds_write_b16 v220, v4 offset:448
	ds_read_u16 v4, v220 offset:1024
	ds_read_u16 v5, v220 offset:1088
	s_waitcnt lgkmcnt(1)
	v_lshlrev_b32_e32 v4, 16, v4
	v_mul_f32_e32 v6, 0xbfb8aa3b, v4
	v_exp_f32_e32 v6, v6
	s_waitcnt lgkmcnt(0)
	v_lshlrev_b32_e32 v5, 16, v5
	v_add_f32_e32 v6, 1.0, v6
	v_div_scale_f32 v7, s[0:1], v6, v6, v4
	s_nop 0
	v_rcp_f32_e32 v7, v6
	s_nop 0
	v_mul_f32_e32 v4, v4, v7
	v_mul_f32_e32 v4, v52, v4
	v_cvt_pk_bf16_f32 v4, v4, s0
	ds_write_b16 v220, v4 offset:1024
	v_mul_f32_e32 v4, 0xbfb8aa3b, v5
	v_exp_f32_e32 v4, v4
	s_nop 0
	v_add_f32_e32 v4, 1.0, v4
	v_div_scale_f32 v6, s[0:1], v4, v4, v5
	s_nop 0
	v_rcp_f32_e32 v4, v4
	s_nop 0
	v_mul_f32_e32 v4, v5, v4
	v_mul_f32_e32 v4, v51, v4
	v_cvt_pk_bf16_f32 v4, v4, s0
	ds_write_b16 v220, v4 offset:1088
	ds_read_u16 v4, v220 offset:1152
	ds_read_u16 v5, v220 offset:1216
	s_waitcnt lgkmcnt(1)
	v_lshlrev_b32_e32 v4, 16, v4
	v_mul_f32_e32 v6, 0xbfb8aa3b, v4
	v_exp_f32_e32 v6, v6
	s_waitcnt lgkmcnt(0)
	v_lshlrev_b32_e32 v5, 16, v5
	v_add_f32_e32 v6, 1.0, v6
	v_div_scale_f32 v7, s[0:1], v6, v6, v4
	s_nop 0
	v_rcp_f32_e32 v7, v6
	s_nop 0
	v_mul_f32_e32 v4, v4, v7
	v_mul_f32_e32 v4, v50, v4
	v_cvt_pk_bf16_f32 v4, v4, s0
	ds_write_b16 v220, v4 offset:1152
	v_mul_f32_e32 v4, 0xbfb8aa3b, v5
	v_exp_f32_e32 v4, v4
	s_nop 0
	v_add_f32_e32 v4, 1.0, v4
	v_div_scale_f32 v6, s[0:1], v4, v4, v5
	s_nop 0
	v_rcp_f32_e32 v4, v4
	s_nop 0
	v_mul_f32_e32 v4, v5, v4
	v_mul_f32_e32 v4, v49, v4
	v_cvt_pk_bf16_f32 v4, v4, s0
	ds_write_b16 v220, v4 offset:1216
	ds_read_u16 v4, v220 offset:1280
	ds_read_u16 v5, v220 offset:1344
	s_waitcnt lgkmcnt(1)
	v_lshlrev_b32_e32 v4, 16, v4
	v_mul_f32_e32 v6, 0xbfb8aa3b, v4
	v_exp_f32_e32 v6, v6
	s_waitcnt lgkmcnt(0)
	v_lshlrev_b32_e32 v5, 16, v5
	v_add_f32_e32 v6, 1.0, v6
	v_div_scale_f32 v7, s[0:1], v6, v6, v4
	s_nop 0
	v_rcp_f32_e32 v7, v6
	s_nop 0
	v_mul_f32_e32 v4, v4, v7
	v_mul_f32_e32 v4, v48, v4
	v_cvt_pk_bf16_f32 v4, v4, s0
	ds_write_b16 v220, v4 offset:1280
	v_mul_f32_e32 v4, 0xbfb8aa3b, v5
	v_exp_f32_e32 v4, v4
	s_nop 0
	v_add_f32_e32 v4, 1.0, v4
	v_div_scale_f32 v6, s[0:1], v4, v4, v5
	s_nop 0
	v_rcp_f32_e32 v4, v4
	s_nop 0
	v_mul_f32_e32 v4, v5, v4
	v_mul_f32_e32 v4, v46, v4
	v_cvt_pk_bf16_f32 v4, v4, s0
	ds_write_b16 v220, v4 offset:1344
	ds_read_u16 v4, v220 offset:1408
	s_waitcnt lgkmcnt(0)
	v_lshlrev_b32_e32 v5, 16, v4
	v_mul_f32_e32 v6, 0xbfb8aa3b, v5
	v_exp_f32_e32 v6, v6
	ds_read_u16 v4, v220 offset:1472
	v_add_f32_e32 v6, 1.0, v6
	v_div_scale_f32 v7, s[0:1], v6, v6, v5
	s_waitcnt lgkmcnt(0)
; #define LAS __attribute__((address_space(3)))
; DI unsigned cvtpk(float lo, float hi) { f32x2 v = {lo, hi}; bf16x2_t b = __builtin_convertvector(v, bf16x2_t); return __builtin_bit_cast(unsigned, b); }
; DI float bf2f(bf16 b) { return __uint_as_float(((unsigned)b) << 16); }
; DI float siluf_(float x) { return x / (1.f + __expf(-x)); }
; DI void nsa_unit(const Ctx& c0, int b, int g, int i, LAS unsigned char* lds) {
;     ...
;       for (int rg = 0; rg < 16; ++rg) { LAS bf16* e = (LAS bf16*)(S + ((rg & 3) + 8 * (rg >> 2) + 4 * hi) * 128 + r * 2);
;           const float z0 = bf2f(e[0]), z1 = bf2f(e[32]);
;           e[0] = (bf16)(cvtpk(ca0[rg] * siluf_(z0), 0.f) & 0xffffu);
;           e[32] = (bf16)(cvtpk(ca1[rg] * siluf_(z1), 0.f) & 0xffffu); }
	v_lshlrev_b32_e32 v4, 16, v4
	v_rcp_f32_e32 v7, v6
	s_nop 0
	v_mul_f32_e32 v5, v5, v7
	v_mul_f32_e32 v5, v45, v5
	v_cvt_pk_bf16_f32 v5, v5, s0
	ds_write_b16 v220, v5 offset:1408
	v_mul_f32_e32 v5, 0xbfb8aa3b, v4
	v_exp_f32_e32 v5, v5
	s_nop 0
	v_add_f32_e32 v5, 1.0, v5
	v_div_scale_f32 v6, s[0:1], v5, v5, v4
	s_nop 0
	v_rcp_f32_e32 v6, v5
	s_nop 0
	v_mul_f32_e32 v4, v4, v6
	v_mul_f32_e32 v4, v44, v4
	v_cvt_pk_bf16_f32 v4, v4, s0
	ds_write_b16 v220, v4 offset:1472
	ds_read_u16 v4, v220 offset:2048
	ds_read_u16 v5, v220 offset:2112
	s_waitcnt lgkmcnt(1)
	v_lshlrev_b32_e32 v4, 16, v4
	v_mul_f32_e32 v6, 0xbfb8aa3b, v4
	v_exp_f32_e32 v6, v6
	s_waitcnt lgkmcnt(0)
	v_lshlrev_b32_e32 v5, 16, v5
	v_add_f32_e32 v6, 1.0, v6
	v_div_scale_f32 v7, s[0:1], v6, v6, v4
	s_nop 0
	v_rcp_f32_e32 v7, v6
	s_nop 0
	v_mul_f32_e32 v4, v4, v7
	v_mul_f32_e32 v4, v27, v4
	v_cvt_pk_bf16_f32 v4, v4, s0
	ds_write_b16 v220, v4 offset:2048
	v_mul_f32_e32 v4, 0xbfb8aa3b, v5
	v_exp_f32_e32 v4, v4
	s_nop 0
	v_add_f32_e32 v4, 1.0, v4
	v_div_scale_f32 v6, s[0:1], v4, v4, v5
	s_nop 0
	v_rcp_f32_e32 v4, v4
	s_nop 0
	v_mul_f32_e32 v4, v5, v4
	v_mul_f32_e32 v4, v26, v4
	v_cvt_pk_bf16_f32 v4, v4, s0
	ds_write_b16 v220, v4 offset:2112
	ds_read_u16 v4, v220 offset:2176
	ds_read_u16 v5, v220 offset:2240
	s_waitcnt lgkmcnt(1)
	v_lshlrev_b32_e32 v4, 16, v4
	v_mul_f32_e32 v6, 0xbfb8aa3b, v4
	v_exp_f32_e32 v6, v6
	s_waitcnt lgkmcnt(0)
	v_lshlrev_b32_e32 v5, 16, v5
	v_add_f32_e32 v6, 1.0, v6
	v_div_scale_f32 v7, s[0:1], v6, v6, v4
	s_nop 0
	v_rcp_f32_e32 v7, v6
	s_nop 0
	v_mul_f32_e32 v4, v4, v7
	v_mul_f32_e32 v4, v25, v4
	v_cvt_pk_bf16_f32 v4, v4, s0
	ds_write_b16 v220, v4 offset:2176
	v_mul_f32_e32 v4, 0xbfb8aa3b, v5
	v_exp_f32_e32 v4, v4
	s_nop 0
	v_add_f32_e32 v4, 1.0, v4
	v_div_scale_f32 v6, s[0:1], v4, v4, v5
	s_nop 0
	v_rcp_f32_e32 v4, v4
	s_nop 0
	v_mul_f32_e32 v4, v5, v4
	v_mul_f32_e32 v4, v24, v4
	v_cvt_pk_bf16_f32 v4, v4, s0
	ds_write_b16 v220, v4 offset:2240
	ds_read_u16 v4, v220 offset:2304
	ds_read_u16 v5, v220 offset:2368
	s_waitcnt lgkmcnt(1)
	v_lshlrev_b32_e32 v4, 16, v4
	v_mul_f32_e32 v6, 0xbfb8aa3b, v4
	v_exp_f32_e32 v6, v6
	s_waitcnt lgkmcnt(0)
	v_lshlrev_b32_e32 v5, 16, v5
	v_add_f32_e32 v6, 1.0, v6
	v_div_scale_f32 v7, s[0:1], v6, v6, v4
	s_nop 0
	v_rcp_f32_e32 v7, v6
	s_nop 0
	v_mul_f32_e32 v4, v4, v7
	v_mul_f32_e32 v4, v23, v4
	v_cvt_pk_bf16_f32 v4, v4, s0
	ds_write_b16 v220, v4 offset:2304
	v_mul_f32_e32 v4, 0xbfb8aa3b, v5
	v_exp_f32_e32 v4, v4
	s_nop 0
	v_add_f32_e32 v4, 1.0, v4
	v_div_scale_f32 v6, s[0:1], v4, v4, v5
	s_nop 0
	v_rcp_f32_e32 v4, v4
	s_nop 0
	v_mul_f32_e32 v4, v5, v4
	v_mul_f32_e32 v4, v22, v4
	v_cvt_pk_bf16_f32 v4, v4, s0
	ds_write_b16 v220, v4 offset:2368
	ds_read_u16 v4, v220 offset:2432
	ds_read_u16 v5, v220 offset:2496
	s_waitcnt lgkmcnt(1)
	v_lshlrev_b32_e32 v4, 16, v4
	v_mul_f32_e32 v6, 0xbfb8aa3b, v4
	v_exp_f32_e32 v6, v6
	s_waitcnt lgkmcnt(0)
	v_lshlrev_b32_e32 v5, 16, v5
	v_add_f32_e32 v6, 1.0, v6
	v_div_scale_f32 v7, s[0:1], v6, v6, v4
	s_nop 0
	v_rcp_f32_e32 v7, v6
	s_nop 0
	v_mul_f32_e32 v4, v4, v7
	v_mul_f32_e32 v4, v21, v4
	v_cvt_pk_bf16_f32 v4, v4, s0
	ds_write_b16 v220, v4 offset:2432
	v_mul_f32_e32 v4, 0xbfb8aa3b, v5
	v_exp_f32_e32 v4, v4
	s_nop 0
	v_add_f32_e32 v4, 1.0, v4
	v_div_scale_f32 v6, s[0:1], v4, v4, v5
	s_nop 0
	v_rcp_f32_e32 v4, v4
	s_nop 0
	v_mul_f32_e32 v4, v5, v4
	v_mul_f32_e32 v4, v15, v4
	v_cvt_pk_bf16_f32 v4, v4, s0
	ds_write_b16 v220, v4 offset:2496
	ds_read_u16 v4, v220 offset:3072
	ds_read_u16 v5, v220 offset:3136
	s_waitcnt lgkmcnt(1)
; #define LAS __attribute__((address_space(3)))
; #define LDS_WAIT() asm volatile("s_waitcnt lgkmcnt(0)" ::: "memory")
; DI unsigned cvtpk(float lo, float hi) { f32x2 v = {lo, hi}; bf16x2_t b = __builtin_convertvector(v, bf16x2_t); return __builtin_bit_cast(unsigned, b); }
; DI float bf2f(bf16 b) { return __uint_as_float(((unsigned)b) << 16); }
; DI float siluf_(float x) { return x / (1.f + __expf(-x)); }
; DI void nsa_unit(const Ctx& c0, int b, int g, int i, LAS unsigned char* lds) {
;     ...
;       for (int rg = 0; rg < 16; ++rg) { LAS bf16* e = (LAS bf16*)(S + ((rg & 3) + 8 * (rg >> 2) + 4 * hi) * 128 + r * 2);
;           const float z0 = bf2f(e[0]), z1 = bf2f(e[32]);
;           e[0] = (bf16)(cvtpk(ca0[rg] * siluf_(z0), 0.f) & 0xffffu);
;           e[32] = (bf16)(cvtpk(ca1[rg] * siluf_(z1), 0.f) & 0xffffu); }
;       LDS_WAIT();
; #pragma unroll
;       for (int it = 0; it < 4; ++it) { const int rw = 8 * it + (lane >> 3), ch = lane & 7;
;           *(u32x4*)(ong + (size_t)rw * 512 + ch * 8) = *(const LAS u32x4*)(S + rw * 128 + ch * 16); }
;       LDS_WAIT(); }
	v_lshlrev_b32_e32 v4, 16, v4
	v_mul_f32_e32 v6, 0xbfb8aa3b, v4
	v_exp_f32_e32 v6, v6
	s_waitcnt lgkmcnt(0)
	v_lshlrev_b32_e32 v5, 16, v5
	v_add_f32_e32 v6, 1.0, v6
	v_div_scale_f32 v7, s[0:1], v6, v6, v4
	s_nop 0
	v_rcp_f32_e32 v7, v6
	s_nop 0
	v_mul_f32_e32 v4, v4, v7
	v_mul_f32_e32 v4, v20, v4
	v_cvt_pk_bf16_f32 v4, v4, s0
	ds_write_b16 v220, v4 offset:3072
	v_mul_f32_e32 v4, 0xbfb8aa3b, v5
	v_exp_f32_e32 v4, v4
	s_nop 0
	v_add_f32_e32 v4, 1.0, v4
	v_div_scale_f32 v6, s[0:1], v4, v4, v5
	s_nop 0
	v_rcp_f32_e32 v4, v4
	s_nop 0
	v_mul_f32_e32 v4, v5, v4
	v_mul_f32_e32 v4, v14, v4
	v_cvt_pk_bf16_f32 v4, v4, s0
	ds_write_b16 v220, v4 offset:3136
	ds_read_u16 v4, v220 offset:3200
	ds_read_u16 v5, v220 offset:3264
	s_waitcnt lgkmcnt(1)
	v_lshlrev_b32_e32 v4, 16, v4
	v_mul_f32_e32 v6, 0xbfb8aa3b, v4
	v_exp_f32_e32 v6, v6
	s_waitcnt lgkmcnt(0)
	v_lshlrev_b32_e32 v5, 16, v5
	v_add_f32_e32 v6, 1.0, v6
	v_div_scale_f32 v7, s[0:1], v6, v6, v4
	s_nop 0
	v_rcp_f32_e32 v7, v6
	s_nop 0
	v_mul_f32_e32 v4, v4, v7
	v_mul_f32_e32 v4, v13, v4
	v_cvt_pk_bf16_f32 v4, v4, s0
	ds_write_b16 v220, v4 offset:3200
	v_mul_f32_e32 v4, 0xbfb8aa3b, v5
	v_exp_f32_e32 v4, v4
	s_nop 0
	v_add_f32_e32 v4, 1.0, v4
	v_div_scale_f32 v6, s[0:1], v4, v4, v5
	s_nop 0
	v_rcp_f32_e32 v4, v4
	s_nop 0
	v_mul_f32_e32 v4, v5, v4
	v_mul_f32_e32 v4, v12, v4
	v_cvt_pk_bf16_f32 v4, v4, s0
	ds_write_b16 v220, v4 offset:3264
	ds_read_u16 v4, v220 offset:3328
	ds_read_u16 v5, v220 offset:3392
	s_waitcnt lgkmcnt(1)
	v_lshlrev_b32_e32 v4, 16, v4
	v_mul_f32_e32 v6, 0xbfb8aa3b, v4
	v_exp_f32_e32 v6, v6
	s_waitcnt lgkmcnt(0)
	v_lshlrev_b32_e32 v5, 16, v5
	v_add_f32_e32 v6, 1.0, v6
	v_div_scale_f32 v7, s[0:1], v6, v6, v4
	s_nop 0
	v_rcp_f32_e32 v7, v6
	s_nop 0
	v_mul_f32_e32 v4, v4, v7
	v_mul_f32_e32 v4, v10, v4
	v_cvt_pk_bf16_f32 v4, v4, s0
	ds_write_b16 v220, v4 offset:3328
	v_mul_f32_e32 v4, 0xbfb8aa3b, v5
	v_exp_f32_e32 v4, v4
	s_nop 0
	v_add_f32_e32 v4, 1.0, v4
	v_div_scale_f32 v6, s[0:1], v4, v4, v5
	s_nop 0
	v_rcp_f32_e32 v4, v4
	s_nop 0
	v_mul_f32_e32 v4, v5, v4
	v_mul_f32_e32 v4, v11, v4
	v_cvt_pk_bf16_f32 v4, v4, s0
	ds_write_b16 v220, v4 offset:3392
	ds_read_u16 v4, v220 offset:3456
	ds_read_u16 v5, v220 offset:3520
	s_waitcnt lgkmcnt(1)
	v_lshlrev_b32_e32 v4, 16, v4
	v_mul_f32_e32 v6, 0xbfb8aa3b, v4
	v_exp_f32_e32 v6, v6
	s_waitcnt lgkmcnt(0)
	v_lshlrev_b32_e32 v5, 16, v5
	v_add_f32_e32 v6, 1.0, v6
	v_div_scale_f32 v7, s[0:1], v6, v6, v4
	s_nop 0
	v_rcp_f32_e32 v7, v6
	s_nop 0
	v_mul_f32_e32 v4, v4, v7
	v_mul_f32_e32 v2, v2, v4
	v_cvt_pk_bf16_f32 v2, v2, s0
	ds_write_b16 v220, v2 offset:3456
	v_mul_f32_e32 v2, 0xbfb8aa3b, v5
	v_exp_f32_e32 v2, v2
	s_nop 0
	v_add_f32_e32 v2, 1.0, v2
	v_div_scale_f32 v4, s[0:1], v2, v2, v5
	s_nop 0
	v_rcp_f32_e32 v2, v2
	s_nop 0
	v_mul_f32_e32 v2, v5, v2
	v_mul_f32_e32 v1, v1, v2
	v_cvt_pk_bf16_f32 v1, v1, s0
	ds_write_b16 v220, v1 offset:3520
	s_waitcnt lgkmcnt(0)
	ds_read_b128 v[4:7], v216
	s_mov_b64 s[0:1], 0xd500000
	v_lshl_add_u64 v[8:9], v[8:9], 0, s[0:1]
	v_lshl_add_u64 v[10:11], v[8:9], 0, v[126:127]
	s_waitcnt lgkmcnt(0)
	global_store_dwordx4 v[10:11], v[4:7], off
	ds_read_b128 v[4:7], v217
	v_lshl_add_u64 v[10:11], v[8:9], 0, v[128:129]
	s_waitcnt lgkmcnt(0)
	global_store_dwordx4 v[10:11], v[4:7], off
	ds_read_b128 v[4:7], v218
	v_lshl_add_u64 v[10:11], v[8:9], 0, v[130:131]
	v_lshl_add_u64 v[8:9], v[8:9], 0, v[132:133]
	s_waitcnt lgkmcnt(0)
	global_store_dwordx4 v[10:11], v[4:7], off
	ds_read_b128 v[4:7], v219
	s_waitcnt lgkmcnt(0)
	global_store_dwordx4 v[8:9], v[4:7], off
	s_waitcnt lgkmcnt(0)
	s_cbranch_scc1 .LBB0_538

; #define LAS __attribute__((address_space(3)))
; #define LDS_WAIT() asm volatile("s_waitcnt lgkmcnt(0)" ::: "memory")
; DI float bflo(unsigned w) { return __uint_as_float(w << 16); }
; DI float bfhi(unsigned w) { return __uint_as_float(w & 0xffff0000u); }
; DI void branch_fold(ASt& st, float gate, bool may_be_empty, LAS float* wsf, int lane) {
;     ...
;     LDS_WAIT();
; #pragma unroll
;     for (int g4 = 0; g4 < 4; ++g4) { const f32x4 f = *(const LAS f32x4*)(wsf + 8 * g4 + 4 * hi);
; #pragma unroll
;         for (int k = 0; k < 4; ++k) { st.o0[4 * g4 + k] *= f[k]; st.o1[4 * g4 + k] *= f[k]; } }
; DI void nsa_unit(const Ctx& c0, int b, int g, int i, LAS unsigned char* lds) {
;     ...
;         branch_fold(st, g_w2, false, wsf, lane);
; #pragma unroll
;         for (int rg = 0; rg < 16; ++rg) { const unsigned w = OC[rg * 64]; ca0[rg] = (OACC[rg * 64] + st.o0[rg]) + bflo(w); ca1[rg] = (OACC[(16 + rg) * 64] + st.o1[rg]) + bfhi(w); }
;         __syncthreads();
;     }
;     ...
;     { const size_t g0 = ((size_t)b * SEQ + i * 64 + 32 * qh) * 512 + head * 64;
;       const bf16* nzg = (const bf16*)(c.ws + O_NZ) + g0; bf16* ong = (bf16*)(c.ws + O_ONSA) + g0;
;       LAS unsigned char* S = lds + A_OC + wid * 4096;
; #pragma unroll
;       for (int it = 0; it < 4; ++it) { const int rw = 8 * it + (lane >> 3), ch = lane & 7;
;           *(LAS u32x4*)(S + rw * 128 + ch * 16) = *(const u32x4*)(nzg + (size_t)rw * 512 + ch * 8); }
.LBB0_1153:
	s_or_b64 exec, exec, s[14:15]
	s_or_b32 s6, s26, s33
	s_add_u32 s14, s4, s6
	s_addc_u32 s15, s5, 0
	s_lshl_b64 s[14:15], s[14:15], 9
	s_add_u32 s14, s14, s22
	s_addc_u32 s15, s15, 0
	s_lshl_b64 s[14:15], s[14:15], 1
	s_add_u32 s0, s0, s14
	s_addc_u32 s1, s1, s15
	v_mov_b32_e32 v135, v3
	v_lshl_add_u64 v[246:247], s[0:1], 0, v[134:135]
	s_mov_b64 s[98:99], 0xb500000
	v_lshl_add_u64 v[246:247], v[246:247], 0, s[98:99]
	v_lshl_add_u64 v[248:249], v[246:247], 0, v[126:127]
	global_load_dwordx4 v[230:233], v[248:249], off
	v_lshl_add_u64 v[248:249], v[246:247], 0, v[128:129]
	global_load_dwordx4 v[234:237], v[248:249], off
	v_lshl_add_u64 v[248:249], v[246:247], 0, v[130:131]
	global_load_dwordx4 v[238:241], v[248:249], off
	v_lshl_add_u64 v[248:249], v[246:247], 0, v[132:133]
	global_load_dwordx4 v[242:245], v[248:249], off
	s_waitcnt lgkmcnt(0)
	ds_read_b128 v[48:51], v192 offset:32768
	ds_read_b128 v[44:47], v192 offset:32800
	ds_read_b128 v[40:43], v192 offset:32832
	ds_read_b128 v[36:39], v192 offset:32864
	ds_read2st64_b32 v[52:53], v203 offset1:1
	ds_read2st64_b32 v[54:55], v190 offset0:144 offset1:145
	ds_read2st64_b32 v[56:57], v190 offset0:160 offset1:161
	s_waitcnt lgkmcnt(0)
	v_lshlrev_b32_e32 v2, 16, v52
	v_fma_f32 v1, v20, v48, v54
	v_add_f32_e32 v60, v1, v2
	v_fma_f32 v1, v4, v48, v56
	v_fmac_f32_e32 v55, v21, v49
	v_fmac_f32_e32 v57, v5, v49
	ds_read2st64_b32 v[4:5], v203 offset0:2 offset1:3
	ds_read2st64_b32 v[20:21], v190 offset0:146 offset1:147
	ds_read2st64_b32 v[48:49], v190 offset0:162 offset1:163
	v_and_b32_e32 v2, 0xffff0000, v52
	v_add_f32_e32 v59, v1, v2
	v_lshlrev_b32_e32 v1, 16, v53
	v_add_f32_e32 v58, v55, v1
	v_and_b32_e32 v1, 0xffff0000, v53
	v_add_f32_e32 v57, v57, v1
	s_waitcnt lgkmcnt(0)
	v_fma_f32 v1, v22, v50, v20
	v_lshlrev_b32_e32 v2, 16, v4
	v_add_f32_e32 v56, v1, v2
	v_fma_f32 v1, v6, v50, v48
	v_and_b32_e32 v2, 0xffff0000, v4
	v_add_f32_e32 v55, v1, v2
	v_fmac_f32_e32 v21, v23, v51
	v_lshlrev_b32_e32 v1, 16, v5
	v_add_f32_e32 v54, v21, v1
	v_fmac_f32_e32 v49, v7, v51
	v_and_b32_e32 v1, 0xffff0000, v5
	ds_read2st64_b32 v[4:5], v203 offset0:4 offset1:5
	ds_read2st64_b32 v[6:7], v190 offset0:148 offset1:149
	ds_read2st64_b32 v[20:21], v190 offset0:164 offset1:165
	v_add_f32_e32 v53, v49, v1
	s_waitcnt lgkmcnt(0)
	v_lshlrev_b32_e32 v2, 16, v4
	v_fma_f32 v1, v24, v44, v6
	v_add_f32_e32 v52, v1, v2
	v_fma_f32 v1, v8, v44, v20
	v_and_b32_e32 v2, 0xffff0000, v4
	v_add_f32_e32 v51, v1, v2
	v_fmac_f32_e32 v7, v25, v45
	v_lshlrev_b32_e32 v1, 16, v5
	v_add_f32_e32 v50, v7, v1
	v_and_b32_e32 v1, 0xffff0000, v5
	ds_read2st64_b32 v[4:5], v203 offset0:6 offset1:7
	ds_read2st64_b32 v[6:7], v190 offset0:150 offset1:151
	v_fmac_f32_e32 v21, v9, v45
	ds_read2st64_b32 v[8:9], v190 offset0:166 offset1:167
	v_add_f32_e32 v49, v21, v1
	s_waitcnt lgkmcnt(0)
	v_lshlrev_b32_e32 v2, 16, v4
	v_fma_f32 v1, v26, v46, v6
	v_add_f32_e32 v48, v1, v2
	v_fma_f32 v1, v10, v46, v8
	v_and_b32_e32 v2, 0xffff0000, v4
	v_add_f32_e32 v46, v1, v2
	v_fmac_f32_e32 v7, v27, v47
	v_lshlrev_b32_e32 v1, 16, v5
	v_add_f32_e32 v45, v7, v1
	v_fmac_f32_e32 v9, v11, v47
	v_and_b32_e32 v1, 0xffff0000, v5
	ds_read2st64_b32 v[4:5], v203 offset0:8 offset1:9
	ds_read2st64_b32 v[6:7], v190 offset0:152 offset1:153
	v_add_f32_e32 v44, v9, v1
	ds_read2st64_b32 v[8:9], v190 offset0:168 offset1:169
	s_waitcnt lgkmcnt(0)
	v_lshlrev_b32_e32 v2, 16, v4
	v_fma_f32 v1, v28, v40, v6
	v_add_f32_e32 v27, v1, v2
	v_fma_f32 v1, v12, v40, v8
	v_and_b32_e32 v2, 0xffff0000, v4
	v_add_f32_e32 v26, v1, v2
	v_fmac_f32_e32 v7, v29, v41
	v_lshlrev_b32_e32 v1, 16, v5
	v_add_f32_e32 v25, v7, v1
	v_fmac_f32_e32 v9, v13, v41
	v_and_b32_e32 v1, 0xffff0000, v5
	ds_read2st64_b32 v[4:5], v203 offset0:10 offset1:11
	ds_read2st64_b32 v[6:7], v190 offset0:154 offset1:155
	v_add_f32_e32 v24, v9, v1
	ds_read2st64_b32 v[8:9], v190 offset0:170 offset1:171
	s_waitcnt lgkmcnt(0)
	v_lshlrev_b32_e32 v2, 16, v4
	v_fma_f32 v1, v30, v42, v6
	v_add_f32_e32 v23, v1, v2
	v_fma_f32 v1, v14, v42, v8
	v_and_b32_e32 v2, 0xffff0000, v4
	v_add_f32_e32 v22, v1, v2
	v_fmac_f32_e32 v7, v31, v43
	v_lshlrev_b32_e32 v1, 16, v5
	v_add_f32_e32 v21, v7, v1
	v_fmac_f32_e32 v9, v15, v43
	v_and_b32_e32 v1, 0xffff0000, v5
	ds_read2st64_b32 v[4:5], v203 offset0:12 offset1:13
	ds_read2st64_b32 v[6:7], v190 offset0:156 offset1:157
	v_add_f32_e32 v15, v9, v1
	ds_read2st64_b32 v[8:9], v190 offset0:172 offset1:173
	s_waitcnt lgkmcnt(0)
	v_lshlrev_b32_e32 v2, 16, v4
	v_fma_f32 v1, v32, v36, v6
	v_add_f32_e32 v20, v1, v2
	v_fma_f32 v1, v16, v36, v8
	v_and_b32_e32 v2, 0xffff0000, v4
	v_add_f32_e32 v14, v1, v2
	v_fmac_f32_e32 v7, v33, v37
	v_lshlrev_b32_e32 v1, 16, v5
	v_add_f32_e32 v13, v7, v1
	v_fmac_f32_e32 v9, v17, v37
	v_and_b32_e32 v1, 0xffff0000, v5
	ds_read2st64_b32 v[4:5], v203 offset0:14 offset1:15
	ds_read2st64_b32 v[6:7], v190 offset0:158 offset1:159
	v_add_f32_e32 v12, v9, v1
	ds_read2st64_b32 v[8:9], v190 offset0:174 offset1:175
	s_waitcnt lgkmcnt(0)
	v_lshlrev_b32_e32 v2, 16, v4
	v_fma_f32 v1, v34, v38, v6
	v_add_f32_e32 v10, v1, v2
	v_fma_f32 v1, v18, v38, v8
	v_and_b32_e32 v2, 0xffff0000, v4
	v_add_f32_e32 v11, v1, v2
	v_fmac_f32_e32 v7, v35, v39
	v_lshlrev_b32_e32 v1, 16, v5
	v_add_f32_e32 v2, v7, v1
	v_fmac_f32_e32 v9, v19, v39
	v_and_b32_e32 v1, 0xffff0000, v5
	v_mov_b32_e32 v135, v3
	v_add_f32_e32 v1, v9, v1
	v_lshl_add_u64 v[8:9], s[0:1], 0, v[134:135]
	s_mov_b64 s[0:1], 0xb500000
	v_lshl_add_u64 v[16:17], v[8:9], 0, s[0:1]
	v_lshl_add_u64 v[4:5], v[16:17], 0, v[126:127]
	s_barrier
; #define LAS __attribute__((address_space(3)))
; #define LDS_WAIT() asm volatile("s_waitcnt lgkmcnt(0)" ::: "memory")
; DI unsigned cvtpk(float lo, float hi) { f32x2 v = {lo, hi}; bf16x2_t b = __builtin_convertvector(v, bf16x2_t); return __builtin_bit_cast(unsigned, b); }
; DI float bf2f(bf16 b) { return __uint_as_float(((unsigned)b) << 16); }
; DI float siluf_(float x) { return x / (1.f + __expf(-x)); }
; DI void nsa_unit(const Ctx& c0, int b, int g, int i, LAS unsigned char* lds) {
;     ...
;       for (int it = 0; it < 4; ++it) { const int rw = 8 * it + (lane >> 3), ch = lane & 7;
;           *(LAS u32x4*)(S + rw * 128 + ch * 16) = *(const u32x4*)(nzg + (size_t)rw * 512 + ch * 8); }
;       LDS_WAIT();
; #pragma unroll
;       for (int rg = 0; rg < 16; ++rg) { LAS bf16* e = (LAS bf16*)(S + ((rg & 3) + 8 * (rg >> 2) + 4 * hi) * 128 + r * 2);
;           const float z0 = bf2f(e[0]), z1 = bf2f(e[32]);
;           e[0] = (bf16)(cvtpk(ca0[rg] * siluf_(z0), 0.f) & 0xffffu);
;           e[32] = (bf16)(cvtpk(ca1[rg] * siluf_(z1), 0.f) & 0xffffu); }
	s_add_i32 s25, s25, 1
	s_cmp_eq_u32 s25, 4
	s_waitcnt vmcnt(0) lgkmcnt(0)
	ds_write_b128 v211, v[230:233]
	ds_write_b128 v212, v[234:237]
	ds_write_b128 v213, v[238:241]
	ds_write_b128 v214, v[242:245]
	s_waitcnt lgkmcnt(0)
	ds_read_u16 v4, v215
	ds_read_u16 v5, v215 offset:64
	s_waitcnt lgkmcnt(1)
	v_lshlrev_b32_e32 v4, 16, v4
	v_mul_f32_e32 v6, 0xbfb8aa3b, v4
	v_exp_f32_e32 v6, v6
	s_waitcnt lgkmcnt(0)
	v_lshlrev_b32_e32 v5, 16, v5
	v_add_f32_e32 v6, 1.0, v6
	v_div_scale_f32 v7, s[0:1], v6, v6, v4
	s_nop 0
	v_rcp_f32_e32 v7, v6
	s_nop 0
	v_mul_f32_e32 v4, v4, v7
	v_mul_f32_e32 v4, v60, v4
	v_cvt_pk_bf16_f32 v4, v4, s0
	ds_write_b16 v215, v4
	v_mul_f32_e32 v4, 0xbfb8aa3b, v5
	v_exp_f32_e32 v4, v4
	s_nop 0
	v_add_f32_e32 v4, 1.0, v4
	v_div_scale_f32 v6, s[0:1], v4, v4, v5
	s_nop 0
	v_rcp_f32_e32 v4, v4
	s_nop 0
	v_mul_f32_e32 v4, v5, v4
	v_mul_f32_e32 v4, v59, v4
	v_cvt_pk_bf16_f32 v4, v4, s0
	ds_write_b16 v215, v4 offset:64
	ds_read_u16 v4, v215 offset:128
	ds_read_u16 v5, v215 offset:192
	s_waitcnt lgkmcnt(1)
	v_lshlrev_b32_e32 v4, 16, v4
	v_mul_f32_e32 v6, 0xbfb8aa3b, v4
	v_exp_f32_e32 v6, v6
	s_waitcnt lgkmcnt(0)
	v_lshlrev_b32_e32 v5, 16, v5
	v_add_f32_e32 v6, 1.0, v6
	v_div_scale_f32 v7, s[0:1], v6, v6, v4
	s_nop 0
	v_rcp_f32_e32 v7, v6
	s_nop 0
	v_mul_f32_e32 v4, v4, v7
	v_mul_f32_e32 v4, v58, v4
	v_cvt_pk_bf16_f32 v4, v4, s0
	ds_write_b16 v215, v4 offset:128
	v_mul_f32_e32 v4, 0xbfb8aa3b, v5
	v_exp_f32_e32 v4, v4
	s_nop 0
	v_add_f32_e32 v4, 1.0, v4
	v_div_scale_f32 v6, s[0:1], v4, v4, v5
	s_nop 0
	v_rcp_f32_e32 v4, v4
	s_nop 0
	v_mul_f32_e32 v4, v5, v4
	v_mul_f32_e32 v4, v57, v4
	v_cvt_pk_bf16_f32 v4, v4, s0
	ds_write_b16 v215, v4 offset:192
	ds_read_u16 v4, v215 offset:256
	ds_read_u16 v5, v215 offset:320
	s_waitcnt lgkmcnt(1)
	v_lshlrev_b32_e32 v4, 16, v4
	v_mul_f32_e32 v6, 0xbfb8aa3b, v4
	v_exp_f32_e32 v6, v6
	s_waitcnt lgkmcnt(0)
	v_lshlrev_b32_e32 v5, 16, v5
	v_add_f32_e32 v6, 1.0, v6
	v_div_scale_f32 v7, s[0:1], v6, v6, v4
	s_nop 0
	v_rcp_f32_e32 v7, v6
	s_nop 0
	v_mul_f32_e32 v4, v4, v7
	v_mul_f32_e32 v4, v56, v4
	v_cvt_pk_bf16_f32 v4, v4, s0
	ds_write_b16 v215, v4 offset:256
	v_mul_f32_e32 v4, 0xbfb8aa3b, v5
	v_exp_f32_e32 v4, v4
	s_nop 0
	v_add_f32_e32 v4, 1.0, v4
	v_div_scale_f32 v6, s[0:1], v4, v4, v5
	s_nop 0
	v_rcp_f32_e32 v4, v4
	s_nop 0
	v_mul_f32_e32 v4, v5, v4
	v_mul_f32_e32 v4, v55, v4
	v_cvt_pk_bf16_f32 v4, v4, s0
	ds_write_b16 v215, v4 offset:320
	ds_read_u16 v4, v215 offset:384
	ds_read_u16 v5, v215 offset:448
	s_waitcnt lgkmcnt(1)
	v_lshlrev_b32_e32 v4, 16, v4
	v_mul_f32_e32 v6, 0xbfb8aa3b, v4
	v_exp_f32_e32 v6, v6
	s_waitcnt lgkmcnt(0)
	v_lshlrev_b32_e32 v5, 16, v5
	v_add_f32_e32 v6, 1.0, v6
	v_div_scale_f32 v7, s[0:1], v6, v6, v4
	s_nop 0
	v_rcp_f32_e32 v7, v6
	s_nop 0
	v_mul_f32_e32 v4, v4, v7
	v_mul_f32_e32 v4, v54, v4
	v_cvt_pk_bf16_f32 v4, v4, s0
	ds_write_b16 v215, v4 offset:384
	v_mul_f32_e32 v4, 0xbfb8aa3b, v5
	v_exp_f32_e32 v4, v4
	s_nop 0
	v_add_f32_e32 v4, 1.0, v4
	v_div_scale_f32 v6, s[0:1], v4, v4, v5
	s_nop 0
	v_rcp_f32_e32 v4, v4
	s_nop 0
	v_mul_f32_e32 v4, v5, v4
	v_mul_f32_e32 v4, v53, v4
	v_cvt_pk_bf16_f32 v4, v4, s0
	ds_write_b16 v215, v4 offset:448
	ds_read_u16 v4, v215 offset:1024
	ds_read_u16 v5, v215 offset:1088
	s_waitcnt lgkmcnt(1)
	v_lshlrev_b32_e32 v4, 16, v4
	v_mul_f32_e32 v6, 0xbfb8aa3b, v4
	v_exp_f32_e32 v6, v6
	s_waitcnt lgkmcnt(0)
	v_lshlrev_b32_e32 v5, 16, v5
	v_add_f32_e32 v6, 1.0, v6
	v_div_scale_f32 v7, s[0:1], v6, v6, v4
	s_nop 0
	v_rcp_f32_e32 v7, v6
	s_nop 0
	v_mul_f32_e32 v4, v4, v7
	v_mul_f32_e32 v4, v52, v4
	v_cvt_pk_bf16_f32 v4, v4, s0
	ds_write_b16 v215, v4 offset:1024
	v_mul_f32_e32 v4, 0xbfb8aa3b, v5
	v_exp_f32_e32 v4, v4
	s_nop 0
	v_add_f32_e32 v4, 1.0, v4
	v_div_scale_f32 v6, s[0:1], v4, v4, v5
	s_nop 0
	v_rcp_f32_e32 v4, v4
	s_nop 0
	v_mul_f32_e32 v4, v5, v4
	v_mul_f32_e32 v4, v51, v4
	v_cvt_pk_bf16_f32 v4, v4, s0
	ds_write_b16 v215, v4 offset:1088
	ds_read_u16 v4, v215 offset:1152
	ds_read_u16 v5, v215 offset:1216
	s_waitcnt lgkmcnt(1)
	v_lshlrev_b32_e32 v4, 16, v4
	v_mul_f32_e32 v6, 0xbfb8aa3b, v4
	v_exp_f32_e32 v6, v6
	s_waitcnt lgkmcnt(0)
	v_lshlrev_b32_e32 v5, 16, v5
	v_add_f32_e32 v6, 1.0, v6
	v_div_scale_f32 v7, s[0:1], v6, v6, v4
	s_nop 0
	v_rcp_f32_e32 v7, v6
	s_nop 0
	v_mul_f32_e32 v4, v4, v7
	v_mul_f32_e32 v4, v50, v4
	v_cvt_pk_bf16_f32 v4, v4, s0
	ds_write_b16 v215, v4 offset:1152
	v_mul_f32_e32 v4, 0xbfb8aa3b, v5
	v_exp_f32_e32 v4, v4
	s_nop 0
	v_add_f32_e32 v4, 1.0, v4
	v_div_scale_f32 v6, s[0:1], v4, v4, v5
	s_nop 0
	v_rcp_f32_e32 v4, v4
	s_nop 0
	v_mul_f32_e32 v4, v5, v4
	v_mul_f32_e32 v4, v49, v4
	v_cvt_pk_bf16_f32 v4, v4, s0
	ds_write_b16 v215, v4 offset:1216
	ds_read_u16 v4, v215 offset:1280
	ds_read_u16 v5, v215 offset:1344
	s_waitcnt lgkmcnt(1)
	v_lshlrev_b32_e32 v4, 16, v4
	v_mul_f32_e32 v6, 0xbfb8aa3b, v4
	v_exp_f32_e32 v6, v6
	s_waitcnt lgkmcnt(0)
	v_lshlrev_b32_e32 v5, 16, v5
	v_add_f32_e32 v6, 1.0, v6
	v_div_scale_f32 v7, s[0:1], v6, v6, v4
	s_nop 0
	v_rcp_f32_e32 v7, v6
	s_nop 0
	v_mul_f32_e32 v4, v4, v7
	v_mul_f32_e32 v4, v48, v4
	v_cvt_pk_bf16_f32 v4, v4, s0
	ds_write_b16 v215, v4 offset:1280
	v_mul_f32_e32 v4, 0xbfb8aa3b, v5
	v_exp_f32_e32 v4, v4
	s_nop 0
	v_add_f32_e32 v4, 1.0, v4
	v_div_scale_f32 v6, s[0:1], v4, v4, v5
	s_nop 0
	v_rcp_f32_e32 v4, v4
	s_nop 0
	v_mul_f32_e32 v4, v5, v4
	v_mul_f32_e32 v4, v46, v4
	v_cvt_pk_bf16_f32 v4, v4, s0
	ds_write_b16 v215, v4 offset:1344
	ds_read_u16 v4, v215 offset:1408
	s_waitcnt lgkmcnt(0)
	v_lshlrev_b32_e32 v5, 16, v4
	v_mul_f32_e32 v6, 0xbfb8aa3b, v5
	v_exp_f32_e32 v6, v6
	ds_read_u16 v4, v215 offset:1472
	v_add_f32_e32 v6, 1.0, v6
	v_div_scale_f32 v7, s[0:1], v6, v6, v5
	s_waitcnt lgkmcnt(0)
; #define LAS __attribute__((address_space(3)))
; DI unsigned cvtpk(float lo, float hi) { f32x2 v = {lo, hi}; bf16x2_t b = __builtin_convertvector(v, bf16x2_t); return __builtin_bit_cast(unsigned, b); }
; DI float bf2f(bf16 b) { return __uint_as_float(((unsigned)b) << 16); }
; DI float siluf_(float x) { return x / (1.f + __expf(-x)); }
; DI void nsa_unit(const Ctx& c0, int b, int g, int i, LAS unsigned char* lds) {
;     ...
;       for (int rg = 0; rg < 16; ++rg) { LAS bf16* e = (LAS bf16*)(S + ((rg & 3) + 8 * (rg >> 2) + 4 * hi) * 128 + r * 2);
;           const float z0 = bf2f(e[0]), z1 = bf2f(e[32]);
;           e[0] = (bf16)(cvtpk(ca0[rg] * siluf_(z0), 0.f) & 0xffffu);
;           e[32] = (bf16)(cvtpk(ca1[rg] * siluf_(z1), 0.f) & 0xffffu); }
	v_lshlrev_b32_e32 v4, 16, v4
	v_rcp_f32_e32 v7, v6
	s_nop 0
	v_mul_f32_e32 v5, v5, v7
	v_mul_f32_e32 v5, v45, v5
	v_cvt_pk_bf16_f32 v5, v5, s0
	ds_write_b16 v215, v5 offset:1408
	v_mul_f32_e32 v5, 0xbfb8aa3b, v4
	v_exp_f32_e32 v5, v5
	s_nop 0
	v_add_f32_e32 v5, 1.0, v5
	v_div_scale_f32 v6, s[0:1], v5, v5, v4
	s_nop 0
	v_rcp_f32_e32 v6, v5
	s_nop 0
	v_mul_f32_e32 v4, v4, v6
	v_mul_f32_e32 v4, v44, v4
	v_cvt_pk_bf16_f32 v4, v4, s0
	ds_write_b16 v215, v4 offset:1472
	ds_read_u16 v4, v215 offset:2048
	ds_read_u16 v5, v215 offset:2112
	s_waitcnt lgkmcnt(1)
	v_lshlrev_b32_e32 v4, 16, v4
	v_mul_f32_e32 v6, 0xbfb8aa3b, v4
	v_exp_f32_e32 v6, v6
	s_waitcnt lgkmcnt(0)
	v_lshlrev_b32_e32 v5, 16, v5
	v_add_f32_e32 v6, 1.0, v6
	v_div_scale_f32 v7, s[0:1], v6, v6, v4
	s_nop 0
	v_rcp_f32_e32 v7, v6
	s_nop 0
	v_mul_f32_e32 v4, v4, v7
	v_mul_f32_e32 v4, v27, v4
	v_cvt_pk_bf16_f32 v4, v4, s0
	ds_write_b16 v215, v4 offset:2048
	v_mul_f32_e32 v4, 0xbfb8aa3b, v5
	v_exp_f32_e32 v4, v4
	s_nop 0
	v_add_f32_e32 v4, 1.0, v4
	v_div_scale_f32 v6, s[0:1], v4, v4, v5
	s_nop 0
	v_rcp_f32_e32 v4, v4
	s_nop 0
	v_mul_f32_e32 v4, v5, v4
	v_mul_f32_e32 v4, v26, v4
	v_cvt_pk_bf16_f32 v4, v4, s0
	ds_write_b16 v215, v4 offset:2112
	ds_read_u16 v4, v215 offset:2176
	ds_read_u16 v5, v215 offset:2240
	s_waitcnt lgkmcnt(1)
	v_lshlrev_b32_e32 v4, 16, v4
	v_mul_f32_e32 v6, 0xbfb8aa3b, v4
	v_exp_f32_e32 v6, v6
	s_waitcnt lgkmcnt(0)
	v_lshlrev_b32_e32 v5, 16, v5
	v_add_f32_e32 v6, 1.0, v6
	v_div_scale_f32 v7, s[0:1], v6, v6, v4
	s_nop 0
	v_rcp_f32_e32 v7, v6
	s_nop 0
	v_mul_f32_e32 v4, v4, v7
	v_mul_f32_e32 v4, v25, v4
	v_cvt_pk_bf16_f32 v4, v4, s0
	ds_write_b16 v215, v4 offset:2176
	v_mul_f32_e32 v4, 0xbfb8aa3b, v5
	v_exp_f32_e32 v4, v4
	s_nop 0
	v_add_f32_e32 v4, 1.0, v4
	v_div_scale_f32 v6, s[0:1], v4, v4, v5
	s_nop 0
	v_rcp_f32_e32 v4, v4
	s_nop 0
	v_mul_f32_e32 v4, v5, v4
	v_mul_f32_e32 v4, v24, v4
	v_cvt_pk_bf16_f32 v4, v4, s0
	ds_write_b16 v215, v4 offset:2240
	ds_read_u16 v4, v215 offset:2304
	ds_read_u16 v5, v215 offset:2368
	s_waitcnt lgkmcnt(1)
	v_lshlrev_b32_e32 v4, 16, v4
	v_mul_f32_e32 v6, 0xbfb8aa3b, v4
	v_exp_f32_e32 v6, v6
	s_waitcnt lgkmcnt(0)
	v_lshlrev_b32_e32 v5, 16, v5
	v_add_f32_e32 v6, 1.0, v6
	v_div_scale_f32 v7, s[0:1], v6, v6, v4
	s_nop 0
	v_rcp_f32_e32 v7, v6
	s_nop 0
	v_mul_f32_e32 v4, v4, v7
	v_mul_f32_e32 v4, v23, v4
	v_cvt_pk_bf16_f32 v4, v4, s0
	ds_write_b16 v215, v4 offset:2304
	v_mul_f32_e32 v4, 0xbfb8aa3b, v5
	v_exp_f32_e32 v4, v4
	s_nop 0
	v_add_f32_e32 v4, 1.0, v4
	v_div_scale_f32 v6, s[0:1], v4, v4, v5
	s_nop 0
	v_rcp_f32_e32 v4, v4
	s_nop 0
	v_mul_f32_e32 v4, v5, v4
	v_mul_f32_e32 v4, v22, v4
	v_cvt_pk_bf16_f32 v4, v4, s0
	ds_write_b16 v215, v4 offset:2368
	ds_read_u16 v4, v215 offset:2432
	ds_read_u16 v5, v215 offset:2496
	s_waitcnt lgkmcnt(1)
	v_lshlrev_b32_e32 v4, 16, v4
	v_mul_f32_e32 v6, 0xbfb8aa3b, v4
	v_exp_f32_e32 v6, v6
	s_waitcnt lgkmcnt(0)
	v_lshlrev_b32_e32 v5, 16, v5
	v_add_f32_e32 v6, 1.0, v6
	v_div_scale_f32 v7, s[0:1], v6, v6, v4
	s_nop 0
	v_rcp_f32_e32 v7, v6
	s_nop 0
	v_mul_f32_e32 v4, v4, v7
	v_mul_f32_e32 v4, v21, v4
	v_cvt_pk_bf16_f32 v4, v4, s0
	ds_write_b16 v215, v4 offset:2432
	v_mul_f32_e32 v4, 0xbfb8aa3b, v5
	v_exp_f32_e32 v4, v4
	s_nop 0
	v_add_f32_e32 v4, 1.0, v4
	v_div_scale_f32 v6, s[0:1], v4, v4, v5
	s_nop 0
	v_rcp_f32_e32 v4, v4
	s_nop 0
	v_mul_f32_e32 v4, v5, v4
	v_mul_f32_e32 v4, v15, v4
	v_cvt_pk_bf16_f32 v4, v4, s0
	ds_write_b16 v215, v4 offset:2496
	ds_read_u16 v4, v215 offset:3072
	ds_read_u16 v5, v215 offset:3136
	s_waitcnt lgkmcnt(1)
; #define LAS __attribute__((address_space(3)))
; #define LDS_WAIT() asm volatile("s_waitcnt lgkmcnt(0)" ::: "memory")
; DI unsigned cvtpk(float lo, float hi) { f32x2 v = {lo, hi}; bf16x2_t b = __builtin_convertvector(v, bf16x2_t); return __builtin_bit_cast(unsigned, b); }
; DI float bf2f(bf16 b) { return __uint_as_float(((unsigned)b) << 16); }
; DI float siluf_(float x) { return x / (1.f + __expf(-x)); }
; DI void nsa_unit(const Ctx& c0, int b, int g, int i, LAS unsigned char* lds) {
;     ...
;       for (int rg = 0; rg < 16; ++rg) { LAS bf16* e = (LAS bf16*)(S + ((rg & 3) + 8 * (rg >> 2) + 4 * hi) * 128 + r * 2);
;           const float z0 = bf2f(e[0]), z1 = bf2f(e[32]);
;           e[0] = (bf16)(cvtpk(ca0[rg] * siluf_(z0), 0.f) & 0xffffu);
;           e[32] = (bf16)(cvtpk(ca1[rg] * siluf_(z1), 0.f) & 0xffffu); }
;       LDS_WAIT();
; #pragma unroll
;       for (int it = 0; it < 4; ++it) { const int rw = 8 * it + (lane >> 3), ch = lane & 7;
;           *(u32x4*)(ong + (size_t)rw * 512 + ch * 8) = *(const LAS u32x4*)(S + rw * 128 + ch * 16); }
;       LDS_WAIT(); }
	v_lshlrev_b32_e32 v4, 16, v4
	v_mul_f32_e32 v6, 0xbfb8aa3b, v4
	v_exp_f32_e32 v6, v6
	s_waitcnt lgkmcnt(0)
	v_lshlrev_b32_e32 v5, 16, v5
	v_add_f32_e32 v6, 1.0, v6
	v_div_scale_f32 v7, s[0:1], v6, v6, v4
	s_nop 0
	v_rcp_f32_e32 v7, v6
	s_nop 0
	v_mul_f32_e32 v4, v4, v7
	v_mul_f32_e32 v4, v20, v4
	v_cvt_pk_bf16_f32 v4, v4, s0
	ds_write_b16 v215, v4 offset:3072
	v_mul_f32_e32 v4, 0xbfb8aa3b, v5
	v_exp_f32_e32 v4, v4
	s_nop 0
	v_add_f32_e32 v4, 1.0, v4
	v_div_scale_f32 v6, s[0:1], v4, v4, v5
	s_nop 0
	v_rcp_f32_e32 v4, v4
	s_nop 0
	v_mul_f32_e32 v4, v5, v4
	v_mul_f32_e32 v4, v14, v4
	v_cvt_pk_bf16_f32 v4, v4, s0
	ds_write_b16 v215, v4 offset:3136
	ds_read_u16 v4, v215 offset:3200
	ds_read_u16 v5, v215 offset:3264
	s_waitcnt lgkmcnt(1)
	v_lshlrev_b32_e32 v4, 16, v4
	v_mul_f32_e32 v6, 0xbfb8aa3b, v4
	v_exp_f32_e32 v6, v6
	s_waitcnt lgkmcnt(0)
	v_lshlrev_b32_e32 v5, 16, v5
	v_add_f32_e32 v6, 1.0, v6
	v_div_scale_f32 v7, s[0:1], v6, v6, v4
	s_nop 0
	v_rcp_f32_e32 v7, v6
	s_nop 0
	v_mul_f32_e32 v4, v4, v7
	v_mul_f32_e32 v4, v13, v4
	v_cvt_pk_bf16_f32 v4, v4, s0
	ds_write_b16 v215, v4 offset:3200
	v_mul_f32_e32 v4, 0xbfb8aa3b, v5
	v_exp_f32_e32 v4, v4
	s_nop 0
	v_add_f32_e32 v4, 1.0, v4
	v_div_scale_f32 v6, s[0:1], v4, v4, v5
	s_nop 0
	v_rcp_f32_e32 v4, v4
	s_nop 0
	v_mul_f32_e32 v4, v5, v4
	v_mul_f32_e32 v4, v12, v4
	v_cvt_pk_bf16_f32 v4, v4, s0
	ds_write_b16 v215, v4 offset:3264
	ds_read_u16 v4, v215 offset:3328
	ds_read_u16 v5, v215 offset:3392
	s_waitcnt lgkmcnt(1)
	v_lshlrev_b32_e32 v4, 16, v4
	v_mul_f32_e32 v6, 0xbfb8aa3b, v4
	v_exp_f32_e32 v6, v6
	s_waitcnt lgkmcnt(0)
	v_lshlrev_b32_e32 v5, 16, v5
	v_add_f32_e32 v6, 1.0, v6
	v_div_scale_f32 v7, s[0:1], v6, v6, v4
	s_nop 0
	v_rcp_f32_e32 v7, v6
	s_nop 0
	v_mul_f32_e32 v4, v4, v7
	v_mul_f32_e32 v4, v10, v4
	v_cvt_pk_bf16_f32 v4, v4, s0
	ds_write_b16 v215, v4 offset:3328
	v_mul_f32_e32 v4, 0xbfb8aa3b, v5
	v_exp_f32_e32 v4, v4
	s_nop 0
	v_add_f32_e32 v4, 1.0, v4
	v_div_scale_f32 v6, s[0:1], v4, v4, v5
	s_nop 0
	v_rcp_f32_e32 v4, v4
	s_nop 0
	v_mul_f32_e32 v4, v5, v4
	v_mul_f32_e32 v4, v11, v4
	v_cvt_pk_bf16_f32 v4, v4, s0
	ds_write_b16 v215, v4 offset:3392
	ds_read_u16 v4, v215 offset:3456
	ds_read_u16 v5, v215 offset:3520
	s_waitcnt lgkmcnt(1)
	v_lshlrev_b32_e32 v4, 16, v4
	v_mul_f32_e32 v6, 0xbfb8aa3b, v4
	v_exp_f32_e32 v6, v6
	s_waitcnt lgkmcnt(0)
	v_lshlrev_b32_e32 v5, 16, v5
	v_add_f32_e32 v6, 1.0, v6
	v_div_scale_f32 v7, s[0:1], v6, v6, v4
	s_nop 0
	v_rcp_f32_e32 v7, v6
	s_nop 0
	v_mul_f32_e32 v4, v4, v7
	v_mul_f32_e32 v2, v2, v4
	v_cvt_pk_bf16_f32 v2, v2, s0
	ds_write_b16 v215, v2 offset:3456
	v_mul_f32_e32 v2, 0xbfb8aa3b, v5
	v_exp_f32_e32 v2, v2
	s_nop 0
	v_add_f32_e32 v2, 1.0, v2
	v_div_scale_f32 v4, s[0:1], v2, v2, v5
	s_nop 0
	v_rcp_f32_e32 v2, v2
	s_nop 0
	v_mul_f32_e32 v2, v5, v2
	v_mul_f32_e32 v1, v1, v2
	v_cvt_pk_bf16_f32 v1, v1, s0
	ds_write_b16 v215, v1 offset:3520
	s_waitcnt lgkmcnt(0)
	ds_read_b128 v[4:7], v211
	s_mov_b64 s[0:1], 0xd500000
	v_lshl_add_u64 v[8:9], v[8:9], 0, s[0:1]
	v_lshl_add_u64 v[10:11], v[8:9], 0, v[126:127]
	s_waitcnt lgkmcnt(0)
	global_store_dwordx4 v[10:11], v[4:7], off
	ds_read_b128 v[4:7], v212
	v_lshl_add_u64 v[10:11], v[8:9], 0, v[128:129]
	s_waitcnt lgkmcnt(0)
	global_store_dwordx4 v[10:11], v[4:7], off
	ds_read_b128 v[4:7], v213
	v_lshl_add_u64 v[10:11], v[8:9], 0, v[130:131]
	v_lshl_add_u64 v[8:9], v[8:9], 0, v[132:133]
	s_waitcnt lgkmcnt(0)
	global_store_dwordx4 v[10:11], v[4:7], off
	ds_read_b128 v[4:7], v214
	s_waitcnt lgkmcnt(0)
	global_store_dwordx4 v[8:9], v[4:7], off
	s_waitcnt lgkmcnt(0)
	s_cbranch_scc1 .LBB0_1151
